# grid barrier: non-leader workgroups sleep a little longer between polls of their release word (fewer idle pollers beside still-working workgroups)
# speedup vs baseline: 1.0012x; 1.0012x over previous
.LBB0_387:
	s_and_b32 s1, s0, 0xff
	s_mov_b64 s[62:63], -1
	s_cmp_lg_u32 s1, 0
	s_mov_b64 s[66:67], -1
	s_sleep 3
	s_cbranch_scc0 .LBB0_390
	s_and_b64 vcc, exec, s[66:67]
	s_cbranch_vccz .LBB0_386
